# v31 with SwiGLU row statistics prefetched at tile start (no exposed round trip in the s5 epilogue)
# speedup vs baseline: 1.0010x; 1.0004x over previous
.LBB0_122:
	v_lshl_add_u32 v242, s2, 8, v153
	v_ashrrev_i32_e32 v243, 31, v242
	v_lshl_add_u64 v[242:243], v[242:243], 3, s[0:1]
	global_load_dwordx2 v[244:245], v[242:243], off
	global_load_dwordx2 v[246:247], v[242:243], off offset:128
	global_load_dwordx2 v[248:249], v[242:243], off offset:256
	global_load_dwordx2 v[250:251], v[242:243], off offset:384
	global_load_dwordx2 v[180:181], v[242:243], off offset:1024
	global_load_dwordx2 v[182:183], v[242:243], off offset:1152
	global_load_dwordx2 v[216:217], v[242:243], off offset:1280
	global_load_dwordx2 v[242:243], v[242:243], off offset:1408
	s_add_i32 s54, s54, 1
	s_mul_i32 s5, s54, s47
	s_mul_hi_u32 s6, s54, s46
	s_add_i32 s6, s6, s5
	s_mul_i32 s5, s54, s46
	v_readlane_b32 s7, v254, 59
	s_add_u32 s16, s5, s7
	s_addc_u32 s17, s6, s29
	v_mov_b64_e32 v[2:3], 0x5d7
	v_cmp_gt_i64_e64 s[6:7], s[16:17], v[2:3]
	s_and_b64 vcc, exec, s[6:7]
	s_cbranch_vccnz .LBB0_124
	s_ashr_i32 s5, s16, 31
	s_lshr_b32 s5, s5, 29
	s_add_i32 s5, s16, s5
	s_ashr_i32 s8, s5, 3
	s_and_b32 s5, s5, -8
	s_sub_i32 s5, s16, s5
	s_cmp_lt_i32 s5, 0
	s_movk_i32 s9, 0xbc
	s_cselect_b32 s9, s9, 0xbb
	s_mul_i32 s5, s5, s9
	s_add_i32 s5, s5, s8
	s_mul_hi_i32 s8, s5, 0x2e8ba2e9
	s_lshr_b32 s9, s8, 31
	s_ashr_i32 s8, s8, 5
	s_add_i32 s8, s8, s9
	s_lshl_b32 s9, s8, 3
	s_sub_i32 s12, 0x44, s9
	s_min_i32 s12, s12, 8
	s_abs_i32 s13, s12
	v_cvt_f32_u32_e32 v2, s13
	s_sub_i32 s15, 0, s13
	s_mulk_i32 s8, 0xb0
	s_sub_i32 s5, s5, s8
	v_rcp_iflag_f32_e32 v2, v2
	s_abs_i32 s8, s5
	s_xor_b32 s14, s5, s12
	s_ashr_i32 s14, s14, 31
	v_mul_f32_e32 v2, 0x4f7ffffe, v2
	v_cvt_u32_f32_e32 v2, v2
	s_nop 0
	v_readfirstlane_b32 s18, v2
	s_mul_i32 s15, s15, s18
	s_mul_hi_u32 s15, s18, s15
	s_add_i32 s18, s18, s15
	s_mul_hi_u32 s15, s8, s18
	s_mul_i32 s18, s15, s13
	s_sub_i32 s8, s8, s18
	s_add_i32 s19, s15, 1
	s_sub_i32 s18, s8, s13
	s_cmp_ge_u32 s8, s13
	s_cselect_b32 s15, s19, s15
	s_cselect_b32 s8, s18, s8
	s_add_i32 s18, s15, 1
	s_cmp_ge_u32 s8, s13
	s_cselect_b32 s8, s18, s15
	s_xor_b32 s8, s8, s14
	s_sub_i32 s8, s8, s14
	s_mul_i32 s12, s8, s12
	s_sub_i32 s5, s5, s12
	s_add_i32 s12, s9, s5

.LBB0_125:
	v_add_u32_e32 v140, s3, v158
	ds_read_b128 v[154:157], v140
	ds_read_b128 v[162:165], v140 offset:1024
	ds_read_b128 v[166:169], v140 offset:2048
	ds_read_b128 v[188:191], v140 offset:3072
	s_add_u32 s22, s20, 0xfffc0080
	s_addc_u32 s23, s21, -1
	s_cmp_eq_u32 s55, 12
	s_cselect_b32 s25, s5, s23
	s_cselect_b32 s24, s13, s22
	s_cselect_b32 s23, s9, s33
	s_cselect_b32 s22, s14, s15
	v_lshl_add_u64 v[140:141], s[20:21], 0, v[136:137]
	s_add_i32 m0, s34, 0xc000
	ds_read_b128 v[192:195], v160
	ds_read_b128 v[196:199], v160 offset:1024
	ds_read_b128 v[200:203], v160 offset:2048
	ds_read_b128 v[204:207], v160 offset:3072
	ds_read_b128 v[208:211], v160 offset:4096
	ds_read_b128 v[212:215], v160 offset:5120
	ds_read_b128 v[218:221], v160 offset:6144
	ds_read_b128 v[222:225], v160 offset:7168
	global_load_lds_dwordx4 v[140:141], off
	v_lshl_add_u64 v[140:141], s[20:21], 0, v[138:139]
	s_add_i32 m0, s34, 0xe000
	s_nop 0
	global_load_lds_dwordx4 v[140:141], off
	s_waitcnt lgkmcnt(8)
	s_barrier
	s_waitcnt lgkmcnt(0)
	s_setprio 1
	s_waitcnt lgkmcnt(0)
	v_mfma_f32_16x16x32_bf16 v[126:129], v[154:157], v[192:195], v[126:129]
	v_mfma_f32_16x16x32_bf16 v[122:125], v[166:169], v[192:195], v[122:125]
	v_mfma_f32_16x16x32_bf16 v[110:113], v[154:157], v[200:203], v[110:113]
	v_mfma_f32_16x16x32_bf16 v[106:109], v[166:169], v[200:203], v[106:109]
	v_mfma_f32_16x16x32_bf16 v[94:97], v[154:157], v[208:211], v[94:97]
	v_mfma_f32_16x16x32_bf16 v[90:93], v[166:169], v[208:211], v[90:93]
	v_mfma_f32_16x16x32_bf16 v[78:81], v[154:157], v[218:221], v[78:81]
	v_mfma_f32_16x16x32_bf16 v[74:77], v[166:169], v[218:221], v[74:77]
	v_mfma_f32_16x16x32_bf16 v[126:129], v[162:165], v[196:199], v[126:129]
	v_mfma_f32_16x16x32_bf16 v[122:125], v[188:191], v[196:199], v[122:125]
	v_mfma_f32_16x16x32_bf16 v[110:113], v[162:165], v[204:207], v[110:113]
	v_mfma_f32_16x16x32_bf16 v[106:109], v[188:191], v[204:207], v[106:109]
	v_mfma_f32_16x16x32_bf16 v[94:97], v[162:165], v[212:215], v[94:97]
	v_mfma_f32_16x16x32_bf16 v[90:93], v[188:191], v[212:215], v[90:93]
	v_mfma_f32_16x16x32_bf16 v[78:81], v[162:165], v[222:225], v[78:81]
	v_mfma_f32_16x16x32_bf16 v[74:77], v[188:191], v[222:225], v[74:77]
	s_setprio 0
	s_barrier
	v_add_u32_e32 v140, s36, v158
	s_mov_b32 m0, s30
	ds_read_b128 v[226:229], v140
	ds_read_b128 v[230:233], v140 offset:1024
	ds_read_b128 v[234:237], v140 offset:2048
	ds_read_b128 v[238:241], v140 offset:3072
	v_lshl_add_u64 v[140:141], s[22:23], 0, v[0:1]
	global_load_lds_dwordx4 v[140:141], off
	v_lshl_add_u64 v[144:145], s[22:23], 0, v[130:131]
	s_mov_b32 m0, s31
	s_nop 0
	global_load_lds_dwordx4 v[144:145], off
	s_barrier
	s_waitcnt lgkmcnt(0)
	s_setprio 1
	s_waitcnt lgkmcnt(0)
	v_mfma_f32_16x16x32_bf16 v[118:121], v[226:229], v[192:195], v[118:121]
	v_mfma_f32_16x16x32_bf16 v[114:117], v[234:237], v[192:195], v[114:117]
	v_mfma_f32_16x16x32_bf16 v[102:105], v[226:229], v[200:203], v[102:105]
	v_mfma_f32_16x16x32_bf16 v[98:101], v[234:237], v[200:203], v[98:101]
	v_mfma_f32_16x16x32_bf16 v[86:89], v[226:229], v[208:211], v[86:89]
	v_mfma_f32_16x16x32_bf16 v[82:85], v[234:237], v[208:211], v[82:85]
	v_mfma_f32_16x16x32_bf16 v[70:73], v[226:229], v[218:221], v[70:73]
	v_mfma_f32_16x16x32_bf16 v[66:69], v[234:237], v[218:221], v[66:69]
	v_mfma_f32_16x16x32_bf16 v[118:121], v[230:233], v[196:199], v[118:121]
	v_mfma_f32_16x16x32_bf16 v[114:117], v[238:241], v[196:199], v[114:117]
	v_mfma_f32_16x16x32_bf16 v[102:105], v[230:233], v[204:207], v[102:105]
	v_mfma_f32_16x16x32_bf16 v[98:101], v[238:241], v[204:207], v[98:101]
	v_mfma_f32_16x16x32_bf16 v[86:89], v[230:233], v[212:215], v[86:89]
	v_mfma_f32_16x16x32_bf16 v[82:85], v[238:241], v[212:215], v[82:85]
	v_mfma_f32_16x16x32_bf16 v[70:73], v[230:233], v[222:225], v[70:73]
	v_mfma_f32_16x16x32_bf16 v[66:69], v[238:241], v[222:225], v[66:69]
	s_setprio 0
	s_mov_b32 m0, s34
	v_lshl_add_u64 v[146:147], s[24:25], 0, v[134:135]
	s_barrier
	ds_read_b128 v[192:195], v160 offset:16384
	ds_read_b128 v[196:199], v160 offset:17408
	ds_read_b128 v[200:203], v160 offset:18432
	ds_read_b128 v[204:207], v160 offset:19456
	ds_read_b128 v[208:211], v160 offset:20480
	ds_read_b128 v[212:215], v160 offset:21504
	ds_read_b128 v[218:221], v160 offset:22528
	ds_read_b128 v[222:225], v160 offset:23552
	global_load_lds_dwordx4 v[146:147], off
	v_lshl_add_u64 v[170:171], s[24:25], 0, v[132:133]
	s_mov_b32 m0, s35
	s_nop 0
	global_load_lds_dwordx4 v[170:171], off
	s_barrier
	s_waitcnt lgkmcnt(0)
	s_setprio 1
	s_waitcnt lgkmcnt(0)
	v_mfma_f32_16x16x32_bf16 v[62:65], v[154:157], v[192:195], v[62:65]
	v_mfma_f32_16x16x32_bf16 v[58:61], v[166:169], v[192:195], v[58:61]
	v_mfma_f32_16x16x32_bf16 v[46:49], v[154:157], v[200:203], v[46:49]
	v_mfma_f32_16x16x32_bf16 v[42:45], v[166:169], v[200:203], v[42:45]
	v_mfma_f32_16x16x32_bf16 v[30:33], v[154:157], v[208:211], v[30:33]
	v_mfma_f32_16x16x32_bf16 v[26:29], v[166:169], v[208:211], v[26:29]
	v_mfma_f32_16x16x32_bf16 v[14:17], v[154:157], v[218:221], v[14:17]
	v_mfma_f32_16x16x32_bf16 v[10:13], v[166:169], v[218:221], v[10:13]
	v_mfma_f32_16x16x32_bf16 v[62:65], v[162:165], v[196:199], v[62:65]
	v_mfma_f32_16x16x32_bf16 v[58:61], v[188:191], v[196:199], v[58:61]
	v_mfma_f32_16x16x32_bf16 v[46:49], v[162:165], v[204:207], v[46:49]
	v_mfma_f32_16x16x32_bf16 v[42:45], v[188:191], v[204:207], v[42:45]
	v_mfma_f32_16x16x32_bf16 v[30:33], v[162:165], v[212:215], v[30:33]
	v_mfma_f32_16x16x32_bf16 v[26:29], v[188:191], v[212:215], v[26:29]
	v_mfma_f32_16x16x32_bf16 v[14:17], v[162:165], v[222:225], v[14:17]
	v_mfma_f32_16x16x32_bf16 v[10:13], v[188:191], v[222:225], v[10:13]
	s_setprio 0
	s_barrier
	s_add_u32 s56, s22, 0x40000
	s_addc_u32 s57, s23, 0
	s_mov_b32 m0, s37
	v_lshl_add_u64 v[154:155], s[56:57], 0, v[0:1]
	global_load_lds_dwordx4 v[154:155], off
	v_lshl_add_u64 v[154:155], s[56:57], 0, v[130:131]
	s_mov_b32 m0, s38
	s_nop 0
	global_load_lds_dwordx4 v[154:155], off
	s_waitcnt vmcnt(6)
	s_barrier
	s_setprio 1
	v_mfma_f32_16x16x32_bf16 v[54:57], v[226:229], v[192:195], v[54:57]
	v_mfma_f32_16x16x32_bf16 v[50:53], v[234:237], v[192:195], v[50:53]
	v_mfma_f32_16x16x32_bf16 v[38:41], v[226:229], v[200:203], v[38:41]
	v_mfma_f32_16x16x32_bf16 v[34:37], v[234:237], v[200:203], v[34:37]
	v_mfma_f32_16x16x32_bf16 v[22:25], v[226:229], v[208:211], v[22:25]
	v_mfma_f32_16x16x32_bf16 v[18:21], v[234:237], v[208:211], v[18:21]
	v_mfma_f32_16x16x32_bf16 v[6:9], v[226:229], v[218:221], v[6:9]
	v_mfma_f32_16x16x32_bf16 v[2:5], v[234:237], v[218:221], v[2:5]
	v_mfma_f32_16x16x32_bf16 v[54:57], v[230:233], v[196:199], v[54:57]
	v_mfma_f32_16x16x32_bf16 v[50:53], v[238:241], v[196:199], v[50:53]
	v_mfma_f32_16x16x32_bf16 v[38:41], v[230:233], v[204:207], v[38:41]
	v_mfma_f32_16x16x32_bf16 v[34:37], v[238:241], v[204:207], v[34:37]
	v_mfma_f32_16x16x32_bf16 v[22:25], v[230:233], v[212:215], v[22:25]
	v_mfma_f32_16x16x32_bf16 v[18:21], v[238:241], v[212:215], v[18:21]
	v_mfma_f32_16x16x32_bf16 v[6:9], v[230:233], v[222:225], v[6:9]
	v_mfma_f32_16x16x32_bf16 v[2:5], v[238:241], v[222:225], v[2:5]
	s_setprio 0
	v_add_u32_e32 v161, s41, v158
	s_barrier
	ds_read_b128 v[154:157], v161
	ds_read_b128 v[162:165], v161 offset:1024
	ds_read_b128 v[166:169], v161 offset:2048
	ds_read_b128 v[188:191], v161 offset:3072
	s_add_u32 s24, s24, 0x40000
	s_addc_u32 s25, s25, 0
	s_mov_b32 m0, s39
	v_lshl_add_u64 v[172:173], s[24:25], 0, v[134:135]
	ds_read_b128 v[192:195], v160 offset:32768
	ds_read_b128 v[196:199], v160 offset:33792
	ds_read_b128 v[200:203], v160 offset:34816
	ds_read_b128 v[204:207], v160 offset:35840
	ds_read_b128 v[208:211], v160 offset:36864
	ds_read_b128 v[212:215], v160 offset:37888
	ds_read_b128 v[218:221], v160 offset:38912
	ds_read_b128 v[222:225], v160 offset:39936
	global_load_lds_dwordx4 v[172:173], off
	v_lshl_add_u64 v[172:173], s[24:25], 0, v[132:133]
	s_mov_b32 m0, s40
	s_nop 0
	global_load_lds_dwordx4 v[172:173], off
	s_waitcnt lgkmcnt(8)
	s_barrier
	s_waitcnt lgkmcnt(0)
	s_setprio 1
	s_waitcnt lgkmcnt(0)
	v_mfma_f32_16x16x32_bf16 v[126:129], v[154:157], v[192:195], v[126:129]
	v_mfma_f32_16x16x32_bf16 v[122:125], v[166:169], v[192:195], v[122:125]
	v_mfma_f32_16x16x32_bf16 v[110:113], v[154:157], v[200:203], v[110:113]
	v_mfma_f32_16x16x32_bf16 v[106:109], v[166:169], v[200:203], v[106:109]
	v_mfma_f32_16x16x32_bf16 v[94:97], v[154:157], v[208:211], v[94:97]
	v_mfma_f32_16x16x32_bf16 v[90:93], v[166:169], v[208:211], v[90:93]
	v_mfma_f32_16x16x32_bf16 v[78:81], v[154:157], v[218:221], v[78:81]
	v_mfma_f32_16x16x32_bf16 v[74:77], v[166:169], v[218:221], v[74:77]
	v_mfma_f32_16x16x32_bf16 v[126:129], v[162:165], v[196:199], v[126:129]
	v_mfma_f32_16x16x32_bf16 v[122:125], v[188:191], v[196:199], v[122:125]
	v_mfma_f32_16x16x32_bf16 v[110:113], v[162:165], v[204:207], v[110:113]
	v_mfma_f32_16x16x32_bf16 v[106:109], v[188:191], v[204:207], v[106:109]
	v_mfma_f32_16x16x32_bf16 v[94:97], v[162:165], v[212:215], v[94:97]
	v_mfma_f32_16x16x32_bf16 v[90:93], v[188:191], v[212:215], v[90:93]
	v_mfma_f32_16x16x32_bf16 v[78:81], v[162:165], v[222:225], v[78:81]
	v_mfma_f32_16x16x32_bf16 v[74:77], v[188:191], v[222:225], v[74:77]
	s_setprio 0
	s_barrier
	s_mov_b32 m0, s42
	v_add_u32_e32 v161, s48, v158
	v_lshl_add_u64 v[140:141], v[140:141], 0, s[66:67]
	ds_read_b128 v[226:229], v161
	ds_read_b128 v[230:233], v161 offset:1024
	ds_read_b128 v[234:237], v161 offset:2048
	ds_read_b128 v[238:241], v161 offset:3072
	global_load_lds_dwordx4 v[140:141], off
	v_lshl_add_u64 v[140:141], v[144:145], 0, s[66:67]
	s_mov_b32 m0, s43
	s_nop 0
	global_load_lds_dwordx4 v[140:141], off
	s_barrier
	s_waitcnt lgkmcnt(0)
	s_setprio 1
	s_waitcnt lgkmcnt(0)
	v_mfma_f32_16x16x32_bf16 v[118:121], v[226:229], v[192:195], v[118:121]
	v_mfma_f32_16x16x32_bf16 v[114:117], v[234:237], v[192:195], v[114:117]
	v_mfma_f32_16x16x32_bf16 v[102:105], v[226:229], v[200:203], v[102:105]
	v_mfma_f32_16x16x32_bf16 v[98:101], v[234:237], v[200:203], v[98:101]
	v_mfma_f32_16x16x32_bf16 v[86:89], v[226:229], v[208:211], v[86:89]
	v_mfma_f32_16x16x32_bf16 v[82:85], v[234:237], v[208:211], v[82:85]
	v_mfma_f32_16x16x32_bf16 v[70:73], v[226:229], v[218:221], v[70:73]
	v_mfma_f32_16x16x32_bf16 v[66:69], v[234:237], v[218:221], v[66:69]
	v_mfma_f32_16x16x32_bf16 v[118:121], v[230:233], v[196:199], v[118:121]
	v_mfma_f32_16x16x32_bf16 v[114:117], v[238:241], v[196:199], v[114:117]
	v_mfma_f32_16x16x32_bf16 v[102:105], v[230:233], v[204:207], v[102:105]
	v_mfma_f32_16x16x32_bf16 v[98:101], v[238:241], v[204:207], v[98:101]
	v_mfma_f32_16x16x32_bf16 v[86:89], v[230:233], v[212:215], v[86:89]
	v_mfma_f32_16x16x32_bf16 v[82:85], v[238:241], v[212:215], v[82:85]
	v_mfma_f32_16x16x32_bf16 v[70:73], v[230:233], v[222:225], v[70:73]
	v_mfma_f32_16x16x32_bf16 v[66:69], v[238:241], v[222:225], v[66:69]
	s_setprio 0
	s_mov_b32 m0, s44
	v_lshl_add_u64 v[140:141], v[146:147], 0, s[66:67]
	s_barrier
	ds_read_b128 v[192:195], v160 offset:49152
	ds_read_b128 v[196:199], v160 offset:50176
	ds_read_b128 v[200:203], v160 offset:51200
	ds_read_b128 v[204:207], v160 offset:52224
	ds_read_b128 v[208:211], v160 offset:53248
	ds_read_b128 v[212:215], v160 offset:54272
	ds_read_b128 v[218:221], v160 offset:55296
	ds_read_b128 v[222:225], v160 offset:56320
	global_load_lds_dwordx4 v[140:141], off
	v_lshl_add_u64 v[140:141], v[170:171], 0, s[66:67]
	s_mov_b32 m0, s45
	s_nop 0
	global_load_lds_dwordx4 v[140:141], off
	s_barrier
	s_waitcnt lgkmcnt(0)
	s_setprio 1
	s_waitcnt lgkmcnt(0)
	v_mfma_f32_16x16x32_bf16 v[62:65], v[154:157], v[192:195], v[62:65]
	v_mfma_f32_16x16x32_bf16 v[58:61], v[166:169], v[192:195], v[58:61]
	v_mfma_f32_16x16x32_bf16 v[46:49], v[154:157], v[200:203], v[46:49]
	v_mfma_f32_16x16x32_bf16 v[42:45], v[166:169], v[200:203], v[42:45]
	v_mfma_f32_16x16x32_bf16 v[30:33], v[154:157], v[208:211], v[30:33]
	v_mfma_f32_16x16x32_bf16 v[26:29], v[166:169], v[208:211], v[26:29]
	v_mfma_f32_16x16x32_bf16 v[14:17], v[154:157], v[218:221], v[14:17]
	v_mfma_f32_16x16x32_bf16 v[10:13], v[166:169], v[218:221], v[10:13]
	v_mfma_f32_16x16x32_bf16 v[62:65], v[162:165], v[196:199], v[62:65]
	v_mfma_f32_16x16x32_bf16 v[58:61], v[188:191], v[196:199], v[58:61]
	v_mfma_f32_16x16x32_bf16 v[46:49], v[162:165], v[204:207], v[46:49]
	v_mfma_f32_16x16x32_bf16 v[42:45], v[188:191], v[204:207], v[42:45]
	v_mfma_f32_16x16x32_bf16 v[30:33], v[162:165], v[212:215], v[30:33]
	v_mfma_f32_16x16x32_bf16 v[26:29], v[188:191], v[212:215], v[26:29]
	v_mfma_f32_16x16x32_bf16 v[14:17], v[162:165], v[222:225], v[14:17]
	v_mfma_f32_16x16x32_bf16 v[10:13], v[188:191], v[222:225], v[10:13]
	s_setprio 0
	s_barrier
	s_add_u32 s22, s22, 0x40080
	s_addc_u32 s23, s23, 0
	s_mov_b32 m0, s52
	v_lshl_add_u64 v[140:141], s[22:23], 0, v[0:1]
	global_load_lds_dwordx4 v[140:141], off
	v_lshl_add_u64 v[140:141], s[22:23], 0, v[130:131]
	s_mov_b32 m0, s53
	s_nop 0
	global_load_lds_dwordx4 v[140:141], off
	s_waitcnt vmcnt(6)
	s_barrier
	s_setprio 1
	v_mfma_f32_16x16x32_bf16 v[54:57], v[226:229], v[192:195], v[54:57]
	v_mfma_f32_16x16x32_bf16 v[50:53], v[234:237], v[192:195], v[50:53]
	v_mfma_f32_16x16x32_bf16 v[38:41], v[226:229], v[200:203], v[38:41]
	v_mfma_f32_16x16x32_bf16 v[34:37], v[234:237], v[200:203], v[34:37]
	v_mfma_f32_16x16x32_bf16 v[22:25], v[226:229], v[208:211], v[22:25]
	v_mfma_f32_16x16x32_bf16 v[18:21], v[234:237], v[208:211], v[18:21]
	v_mfma_f32_16x16x32_bf16 v[6:9], v[226:229], v[218:221], v[6:9]
	v_mfma_f32_16x16x32_bf16 v[2:5], v[234:237], v[218:221], v[2:5]
	v_mfma_f32_16x16x32_bf16 v[54:57], v[230:233], v[196:199], v[54:57]
	v_mfma_f32_16x16x32_bf16 v[50:53], v[238:241], v[196:199], v[50:53]
	v_mfma_f32_16x16x32_bf16 v[38:41], v[230:233], v[204:207], v[38:41]
	v_mfma_f32_16x16x32_bf16 v[34:37], v[238:241], v[204:207], v[34:37]
	v_mfma_f32_16x16x32_bf16 v[22:25], v[230:233], v[212:215], v[22:25]
	v_mfma_f32_16x16x32_bf16 v[18:21], v[238:241], v[212:215], v[18:21]
	v_mfma_f32_16x16x32_bf16 v[6:9], v[230:233], v[222:225], v[6:9]
	v_mfma_f32_16x16x32_bf16 v[2:5], v[238:241], v[222:225], v[2:5]
	s_setprio 0
	s_add_i32 s55, s55, 2
	s_add_u32 s20, s20, 0x100
	s_addc_u32 s21, s21, 0
	s_add_u32 s15, s15, 0x100
	s_addc_u32 s33, s33, 0
	s_cmp_gt_u32 s55, 13
	s_barrier
	s_cbranch_scc0 .LBB0_125
	v_lshl_add_u32 v140, s2, 8, v153
	v_ashrrev_i32_e32 v141, 31, v140
	v_lshl_add_u64 v[154:155], v[140:141], 3, s[0:1]
	v_mov_b64_e32 v[144:145], v[244:245]
	v_lshl_or_b32 v156, s4, 7, v159
	v_ashrrev_i32_e32 v157, 31, v156
	s_movk_i32 s2, 0x1600
	s_mov_b64 s[22:23], s[18:19]
	s_mov_b64 s[20:21], s[16:17]
	v_ffbh_u32_e32 v141, v145
	v_min_u32_e32 v141, 32, v141
	v_lshlrev_b64 v[144:145], v141, v[144:145]
	v_min_u32_e32 v144, 1, v144
	v_or_b32_e32 v144, v145, v144
	v_cvt_f32_u32_e32 v144, v144
	v_sub_u32_e32 v141, 32, v141
	v_ldexp_f32 v141, v144, v141
	v_fmamk_f32 v141, v141, 0x2e800000, v143
	v_cmp_gt_f32_e32 vcc, s90, v141
	v_mul_f32_e32 v144, 0x4b800000, v141
	s_nop 0
	v_cndmask_b32_e32 v141, v141, v144, vcc
	v_rsq_f32_e32 v141, v141
	s_nop 0
	v_mul_f32_e32 v144, 0x45800000, v141
	v_cndmask_b32_e32 v144, v141, v144, vcc
	v_pk_mul_f32 v[126:127], v[126:127], v[144:145] op_sel_hi:[1,0]
	v_pk_mul_f32 v[118:119], v[118:119], v[144:145] op_sel_hi:[1,0]
	v_mul_f32_e32 v141, 0xbfb8aa3b, v126
	v_exp_f32_e32 v141, v141
	v_pk_mul_f32 v[128:129], v[128:129], v[144:145] op_sel_hi:[1,0]
	v_pk_mul_f32 v[120:121], v[120:121], v[144:145] op_sel_hi:[1,0]
	v_pk_mul_f32 v[114:115], v[114:115], v[144:145] op_sel_hi:[1,0]
	v_add_f32_e32 v141, 1.0, v141
	v_rcp_f32_e32 v141, v141
	v_pk_mul_f32 v[124:125], v[124:125], v[144:145] op_sel_hi:[1,0]
	v_pk_mul_f32 v[116:117], v[116:117], v[144:145] op_sel_hi:[1,0]
	v_mul_f32_e32 v126, v126, v141
	v_mul_f32_e32 v118, v118, v126
	v_mul_f32_e32 v126, 0xbfb8aa3b, v127
	v_exp_f32_e32 v126, v126
	s_nop 0
	v_add_f32_e32 v126, 1.0, v126
	v_rcp_f32_e32 v126, v126
	s_nop 0
	v_mul_f32_e32 v126, v127, v126
	v_mul_f32_e32 v119, v119, v126
	v_cvt_pk_bf16_f32 v118, v118, v119
	v_mul_f32_e32 v119, 0xbfb8aa3b, v128
	v_exp_f32_e32 v119, v119
	s_nop 0
	v_add_f32_e32 v119, 1.0, v119
	v_rcp_f32_e32 v119, v119
	s_nop 0
	v_mul_f32_e32 v119, v128, v119
	v_mul_f32_e32 v119, v120, v119
	v_mul_f32_e32 v120, 0xbfb8aa3b, v129
	v_exp_f32_e32 v120, v120
	s_nop 0
	v_add_f32_e32 v120, 1.0, v120
	v_rcp_f32_e32 v120, v120
	s_nop 0
	v_mul_f32_e32 v120, v129, v120
	v_mul_f32_e32 v120, v121, v120
	v_cvt_pk_bf16_f32 v119, v119, v120
	v_pk_mul_f32 v[120:121], v[122:123], v[144:145] op_sel_hi:[1,0]
	s_nop 0
	v_mul_f32_e32 v122, 0xbfb8aa3b, v120
	v_exp_f32_e32 v122, v122
	s_nop 0
	v_add_f32_e32 v122, 1.0, v122
	v_rcp_f32_e32 v122, v122
	s_nop 0
	v_mul_f32_e32 v120, v120, v122
	v_mul_f32_e32 v114, v114, v120
	v_mul_f32_e32 v120, 0xbfb8aa3b, v121
	v_exp_f32_e32 v120, v120
	s_nop 0
	v_add_f32_e32 v120, 1.0, v120
	v_rcp_f32_e32 v120, v120
	s_nop 0
	v_mul_f32_e32 v120, v121, v120
	v_mul_f32_e32 v115, v115, v120
	v_cvt_pk_bf16_f32 v120, v114, v115
	v_mul_f32_e32 v114, 0xbfb8aa3b, v124
	v_mul_f32_e32 v115, 0xbfb8aa3b, v125
	v_exp_f32_e32 v114, v114
	v_exp_f32_e32 v115, v115
	v_add_f32_e32 v114, 1.0, v114
	v_add_f32_e32 v115, 1.0, v115
	v_rcp_f32_e32 v114, v114
	v_rcp_f32_e32 v115, v115
	v_mul_f32_e32 v114, v124, v114
	v_mul_f32_e32 v115, v125, v115
	v_mul_f32_e32 v114, v116, v114
	v_mul_f32_e32 v115, v117, v115
	v_cvt_pk_bf16_f32 v121, v114, v115
	v_mov_b64_e32 v[114:115], s[72:73]
	v_mad_i64_i32 v[122:123], s[4:5], v140, s2, v[114:115]
	v_lshlrev_b64 v[116:117], 1, v[156:157]
	v_lshl_add_u64 v[122:123], v[122:123], 0, v[116:117]
	global_store_dwordx4 v[122:123], v[118:121], off
	s_nop 1
	v_mov_b64_e32 v[118:119], v[246:247]
	s_nop 0
	v_or_b32_e32 v120, 16, v140
	v_ffbh_u32_e32 v121, v119
	v_min_u32_e32 v121, 32, v121
	v_lshlrev_b64 v[118:119], v121, v[118:119]
	v_min_u32_e32 v118, 1, v118
	v_or_b32_e32 v118, v119, v118
	v_cvt_f32_u32_e32 v118, v118
	v_sub_u32_e32 v119, 32, v121
	v_ldexp_f32 v118, v118, v119
	v_fmamk_f32 v118, v118, 0x2e800000, v143
	v_cmp_gt_f32_e32 vcc, s90, v118
	v_mul_f32_e32 v119, 0x4b800000, v118
	s_nop 0
	v_cndmask_b32_e32 v118, v118, v119, vcc
	v_rsq_f32_e32 v118, v118
	s_nop 0
	v_mul_f32_e32 v119, 0x45800000, v118
	v_cndmask_b32_e32 v118, v118, v119, vcc
	v_pk_mul_f32 v[110:111], v[110:111], v[118:119] op_sel_hi:[1,0]
	v_pk_mul_f32 v[112:113], v[112:113], v[118:119] op_sel_hi:[1,0]
	v_pk_mul_f32 v[104:105], v[104:105], v[118:119] op_sel_hi:[1,0]
	v_pk_mul_f32 v[102:103], v[102:103], v[118:119] op_sel_hi:[1,0]
	v_mul_f32_e32 v119, 0xbfb8aa3b, v110
	v_exp_f32_e32 v119, v119
	s_nop 0
	v_add_f32_e32 v119, 1.0, v119
	v_rcp_f32_e32 v119, v119
	s_nop 0
	v_mul_f32_e32 v110, v110, v119
	v_mul_f32_e32 v102, v102, v110
	v_mul_f32_e32 v110, 0xbfb8aa3b, v111
	v_exp_f32_e32 v110, v110
	v_pk_mul_f32 v[98:99], v[98:99], v[118:119] op_sel_hi:[1,0]
	v_pk_mul_f32 v[108:109], v[108:109], v[118:119] op_sel_hi:[1,0]
	v_pk_mul_f32 v[100:101], v[100:101], v[118:119] op_sel_hi:[1,0]
	v_add_f32_e32 v110, 1.0, v110
	v_rcp_f32_e32 v110, v110
	s_nop 0
	v_mul_f32_e32 v110, v111, v110
	v_mul_f32_e32 v103, v103, v110
	v_cvt_pk_bf16_f32 v102, v102, v103
	v_mul_f32_e32 v103, 0xbfb8aa3b, v112
	v_exp_f32_e32 v103, v103
	s_nop 0
	v_add_f32_e32 v103, 1.0, v103
	v_rcp_f32_e32 v103, v103
	s_nop 0
	v_mul_f32_e32 v103, v112, v103
	v_mul_f32_e32 v103, v104, v103
	v_mul_f32_e32 v104, 0xbfb8aa3b, v113
	v_exp_f32_e32 v104, v104
	s_nop 0
	v_add_f32_e32 v104, 1.0, v104
	v_rcp_f32_e32 v104, v104
	s_nop 0
	v_mul_f32_e32 v104, v113, v104
	v_mul_f32_e32 v104, v105, v104
	v_cvt_pk_bf16_f32 v103, v103, v104
	v_pk_mul_f32 v[104:105], v[106:107], v[118:119] op_sel_hi:[1,0]
	s_nop 0
	v_mul_f32_e32 v106, 0xbfb8aa3b, v104
	v_exp_f32_e32 v106, v106
	s_nop 0
	v_add_f32_e32 v106, 1.0, v106
	v_rcp_f32_e32 v106, v106
	s_nop 0
	v_mul_f32_e32 v104, v104, v106
	v_mul_f32_e32 v98, v98, v104
	v_mul_f32_e32 v104, 0xbfb8aa3b, v105
	v_exp_f32_e32 v104, v104
	s_nop 0
	v_add_f32_e32 v104, 1.0, v104
	v_rcp_f32_e32 v104, v104
	s_nop 0
	v_mul_f32_e32 v104, v105, v104
	v_mul_f32_e32 v99, v99, v104
	v_cvt_pk_bf16_f32 v104, v98, v99
	v_mul_f32_e32 v98, 0xbfb8aa3b, v108
	v_mul_f32_e32 v99, 0xbfb8aa3b, v109
	v_exp_f32_e32 v98, v98
	v_exp_f32_e32 v99, v99
	v_add_f32_e32 v98, 1.0, v98
	v_add_f32_e32 v99, 1.0, v99
	v_rcp_f32_e32 v98, v98
	v_rcp_f32_e32 v99, v99
	v_mul_f32_e32 v98, v108, v98
	v_mul_f32_e32 v99, v109, v99
	v_mul_f32_e32 v98, v100, v98
	v_mul_f32_e32 v99, v101, v99
	v_cvt_pk_bf16_f32 v105, v98, v99
	v_mad_i64_i32 v[98:99], s[4:5], v120, s2, v[114:115]
	v_lshl_add_u64 v[98:99], v[98:99], 0, v[116:117]
	global_store_dwordx4 v[98:99], v[102:105], off
	s_nop 1
	v_mov_b64_e32 v[98:99], v[248:249]
	v_or_b32_e32 v100, 32, v140
	v_ffbh_u32_e32 v101, v99
	v_min_u32_e32 v101, 32, v101
	v_lshlrev_b64 v[98:99], v101, v[98:99]
	v_min_u32_e32 v98, 1, v98
	v_or_b32_e32 v98, v99, v98
	v_cvt_f32_u32_e32 v98, v98
	v_sub_u32_e32 v99, 32, v101
	v_ldexp_f32 v98, v98, v99
	v_fmamk_f32 v98, v98, 0x2e800000, v143
	v_cmp_gt_f32_e32 vcc, s90, v98
	v_mul_f32_e32 v99, 0x4b800000, v98
	s_nop 0
	v_cndmask_b32_e32 v98, v98, v99, vcc
	v_rsq_f32_e32 v98, v98
	s_nop 0
	v_mul_f32_e32 v99, 0x45800000, v98
	v_cndmask_b32_e32 v98, v98, v99, vcc
	v_pk_mul_f32 v[94:95], v[94:95], v[98:99] op_sel_hi:[1,0]
	v_pk_mul_f32 v[96:97], v[96:97], v[98:99] op_sel_hi:[1,0]
	v_pk_mul_f32 v[88:89], v[88:89], v[98:99] op_sel_hi:[1,0]
	v_pk_mul_f32 v[86:87], v[86:87], v[98:99] op_sel_hi:[1,0]
	v_mul_f32_e32 v99, 0xbfb8aa3b, v94
	v_exp_f32_e32 v99, v99
	s_nop 0
	v_add_f32_e32 v99, 1.0, v99
	v_rcp_f32_e32 v99, v99
	s_nop 0
	v_mul_f32_e32 v94, v94, v99
	v_mul_f32_e32 v86, v86, v94
	v_mul_f32_e32 v94, 0xbfb8aa3b, v95
	v_exp_f32_e32 v94, v94
	v_pk_mul_f32 v[82:83], v[82:83], v[98:99] op_sel_hi:[1,0]
	v_pk_mul_f32 v[92:93], v[92:93], v[98:99] op_sel_hi:[1,0]
	v_pk_mul_f32 v[84:85], v[84:85], v[98:99] op_sel_hi:[1,0]
	v_add_f32_e32 v94, 1.0, v94
	v_rcp_f32_e32 v94, v94
	s_nop 0
	v_mul_f32_e32 v94, v95, v94
	v_mul_f32_e32 v87, v87, v94
	v_cvt_pk_bf16_f32 v86, v86, v87
	v_mul_f32_e32 v87, 0xbfb8aa3b, v96
	v_exp_f32_e32 v87, v87
	s_nop 0
	v_add_f32_e32 v87, 1.0, v87
	v_rcp_f32_e32 v87, v87
	s_nop 0
	v_mul_f32_e32 v87, v96, v87
	v_mul_f32_e32 v87, v88, v87
	v_mul_f32_e32 v88, 0xbfb8aa3b, v97
	v_exp_f32_e32 v88, v88
	s_nop 0
	v_add_f32_e32 v88, 1.0, v88
	v_rcp_f32_e32 v88, v88
	s_nop 0
	v_mul_f32_e32 v88, v97, v88
	v_mul_f32_e32 v88, v89, v88
	v_cvt_pk_bf16_f32 v87, v87, v88
	v_pk_mul_f32 v[88:89], v[90:91], v[98:99] op_sel_hi:[1,0]
	s_nop 0
	v_mul_f32_e32 v90, 0xbfb8aa3b, v88
	v_exp_f32_e32 v90, v90
	s_nop 0
	v_add_f32_e32 v90, 1.0, v90
	v_rcp_f32_e32 v90, v90
	s_nop 0
	v_mul_f32_e32 v88, v88, v90
	v_mul_f32_e32 v82, v82, v88
	v_mul_f32_e32 v88, 0xbfb8aa3b, v89
	v_exp_f32_e32 v88, v88
	s_nop 0
	v_add_f32_e32 v88, 1.0, v88
	v_rcp_f32_e32 v88, v88
	s_nop 0
	v_mul_f32_e32 v88, v89, v88
	v_mul_f32_e32 v83, v83, v88
	v_cvt_pk_bf16_f32 v88, v82, v83
	v_mul_f32_e32 v82, 0xbfb8aa3b, v92
	v_mul_f32_e32 v83, 0xbfb8aa3b, v93
	v_exp_f32_e32 v82, v82
	v_exp_f32_e32 v83, v83
	v_add_f32_e32 v82, 1.0, v82
	v_add_f32_e32 v83, 1.0, v83
	v_rcp_f32_e32 v82, v82
	v_rcp_f32_e32 v83, v83
	v_mul_f32_e32 v82, v92, v82
	v_mul_f32_e32 v83, v93, v83
	v_mul_f32_e32 v82, v84, v82
	v_mul_f32_e32 v83, v85, v83
	v_cvt_pk_bf16_f32 v89, v82, v83
	v_mad_i64_i32 v[82:83], s[4:5], v100, s2, v[114:115]
	v_lshl_add_u64 v[82:83], v[82:83], 0, v[116:117]
	global_store_dwordx4 v[82:83], v[86:89], off
	s_nop 1
	v_mov_b64_e32 v[82:83], v[250:251]
	v_or_b32_e32 v84, 48, v140
	v_ffbh_u32_e32 v85, v83
	v_min_u32_e32 v85, 32, v85
	v_lshlrev_b64 v[82:83], v85, v[82:83]
	v_min_u32_e32 v82, 1, v82
	v_or_b32_e32 v82, v83, v82
	v_cvt_f32_u32_e32 v82, v82
	v_sub_u32_e32 v83, 32, v85
	v_ldexp_f32 v82, v82, v83
	v_fmamk_f32 v82, v82, 0x2e800000, v143
	v_cmp_gt_f32_e32 vcc, s90, v82
	v_mul_f32_e32 v83, 0x4b800000, v82
	s_nop 0
	v_cndmask_b32_e32 v82, v82, v83, vcc
	v_rsq_f32_e32 v82, v82
	s_nop 0
	v_mul_f32_e32 v83, 0x45800000, v82
	v_cndmask_b32_e32 v82, v82, v83, vcc
	v_pk_mul_f32 v[78:79], v[78:79], v[82:83] op_sel_hi:[1,0]
	v_pk_mul_f32 v[80:81], v[80:81], v[82:83] op_sel_hi:[1,0]
	v_pk_mul_f32 v[72:73], v[72:73], v[82:83] op_sel_hi:[1,0]
	v_pk_mul_f32 v[70:71], v[70:71], v[82:83] op_sel_hi:[1,0]
	v_mul_f32_e32 v83, 0xbfb8aa3b, v78
	v_exp_f32_e32 v83, v83
	s_nop 0
	v_add_f32_e32 v83, 1.0, v83
	v_rcp_f32_e32 v83, v83
	s_nop 0
	v_mul_f32_e32 v78, v78, v83
	v_mul_f32_e32 v70, v70, v78
	v_mul_f32_e32 v78, 0xbfb8aa3b, v79
	v_exp_f32_e32 v78, v78
	v_pk_mul_f32 v[66:67], v[66:67], v[82:83] op_sel_hi:[1,0]
	v_pk_mul_f32 v[76:77], v[76:77], v[82:83] op_sel_hi:[1,0]
	v_pk_mul_f32 v[68:69], v[68:69], v[82:83] op_sel_hi:[1,0]
	v_add_f32_e32 v78, 1.0, v78
	v_rcp_f32_e32 v78, v78
	s_nop 0
	v_mul_f32_e32 v78, v79, v78
	v_mul_f32_e32 v71, v71, v78
	v_cvt_pk_bf16_f32 v70, v70, v71
	v_mul_f32_e32 v71, 0xbfb8aa3b, v80
	v_exp_f32_e32 v71, v71
	s_nop 0
	v_add_f32_e32 v71, 1.0, v71
	v_rcp_f32_e32 v71, v71
	s_nop 0
	v_mul_f32_e32 v71, v80, v71
	v_mul_f32_e32 v71, v72, v71
	v_mul_f32_e32 v72, 0xbfb8aa3b, v81
	v_exp_f32_e32 v72, v72
	s_nop 0
	v_add_f32_e32 v72, 1.0, v72
	v_rcp_f32_e32 v72, v72
	s_nop 0
	v_mul_f32_e32 v72, v81, v72
	v_mul_f32_e32 v72, v73, v72
	v_cvt_pk_bf16_f32 v71, v71, v72
	v_pk_mul_f32 v[72:73], v[74:75], v[82:83] op_sel_hi:[1,0]
	s_nop 0
	v_mul_f32_e32 v74, 0xbfb8aa3b, v72
	v_exp_f32_e32 v74, v74
	s_nop 0
	v_add_f32_e32 v74, 1.0, v74
	v_rcp_f32_e32 v74, v74
	s_nop 0
	v_mul_f32_e32 v72, v72, v74
	v_mul_f32_e32 v66, v66, v72
	v_mul_f32_e32 v72, 0xbfb8aa3b, v73
	v_exp_f32_e32 v72, v72
	s_nop 0
	v_add_f32_e32 v72, 1.0, v72
	v_rcp_f32_e32 v72, v72
	s_nop 0
	v_mul_f32_e32 v72, v73, v72
	v_mul_f32_e32 v67, v67, v72
	v_cvt_pk_bf16_f32 v72, v66, v67
	v_mul_f32_e32 v66, 0xbfb8aa3b, v76
	v_mul_f32_e32 v67, 0xbfb8aa3b, v77
	v_exp_f32_e32 v66, v66
	v_exp_f32_e32 v67, v67
	v_add_f32_e32 v66, 1.0, v66
	v_add_f32_e32 v67, 1.0, v67
	v_rcp_f32_e32 v66, v66
	v_rcp_f32_e32 v67, v67
	v_mul_f32_e32 v66, v76, v66
	v_mul_f32_e32 v67, v77, v67
	v_mul_f32_e32 v66, v68, v66
	v_mul_f32_e32 v67, v69, v67
	v_cvt_pk_bf16_f32 v73, v66, v67
	v_mad_i64_i32 v[66:67], s[4:5], v84, s2, v[114:115]
	v_lshl_add_u64 v[66:67], v[66:67], 0, v[116:117]
	global_store_dwordx4 v[66:67], v[70:73], off
	s_nop 1
	v_mov_b64_e32 v[66:67], v[180:181]
	v_add_u32_e32 v68, 0x80, v140
	v_ffbh_u32_e32 v69, v67
	v_min_u32_e32 v69, 32, v69
	v_lshlrev_b64 v[66:67], v69, v[66:67]
	v_min_u32_e32 v66, 1, v66
	v_or_b32_e32 v66, v67, v66
	v_cvt_f32_u32_e32 v66, v66
	v_sub_u32_e32 v67, 32, v69
	v_ldexp_f32 v66, v66, v67
	v_fmamk_f32 v66, v66, 0x2e800000, v143
	v_cmp_gt_f32_e32 vcc, s90, v66
	v_mul_f32_e32 v67, 0x4b800000, v66
	s_nop 0
	v_cndmask_b32_e32 v66, v66, v67, vcc
	v_rsq_f32_e32 v66, v66
	s_nop 0
	v_mul_f32_e32 v67, 0x45800000, v66
	v_cndmask_b32_e32 v66, v66, v67, vcc
	v_pk_mul_f32 v[62:63], v[62:63], v[66:67] op_sel_hi:[1,0]
	v_pk_mul_f32 v[64:65], v[64:65], v[66:67] op_sel_hi:[1,0]
	v_pk_mul_f32 v[56:57], v[56:57], v[66:67] op_sel_hi:[1,0]
	v_pk_mul_f32 v[54:55], v[54:55], v[66:67] op_sel_hi:[1,0]
	v_mul_f32_e32 v67, 0xbfb8aa3b, v62
	v_exp_f32_e32 v67, v67
	s_nop 0
	v_add_f32_e32 v67, 1.0, v67
	v_rcp_f32_e32 v67, v67
	s_nop 0
	v_mul_f32_e32 v62, v62, v67
	v_mul_f32_e32 v54, v54, v62
	v_mul_f32_e32 v62, 0xbfb8aa3b, v63
	v_exp_f32_e32 v62, v62
	v_pk_mul_f32 v[50:51], v[50:51], v[66:67] op_sel_hi:[1,0]
	v_pk_mul_f32 v[60:61], v[60:61], v[66:67] op_sel_hi:[1,0]
	v_pk_mul_f32 v[52:53], v[52:53], v[66:67] op_sel_hi:[1,0]
	v_add_f32_e32 v62, 1.0, v62
	v_rcp_f32_e32 v62, v62
	s_nop 0
	v_mul_f32_e32 v62, v63, v62
	v_mul_f32_e32 v55, v55, v62
	v_cvt_pk_bf16_f32 v54, v54, v55
	v_mul_f32_e32 v55, 0xbfb8aa3b, v64
	v_exp_f32_e32 v55, v55
	s_nop 0
	v_add_f32_e32 v55, 1.0, v55
	v_rcp_f32_e32 v55, v55
	s_nop 0
	v_mul_f32_e32 v55, v64, v55
	v_mul_f32_e32 v55, v56, v55
	v_mul_f32_e32 v56, 0xbfb8aa3b, v65
	v_exp_f32_e32 v56, v56
	s_nop 0
	v_add_f32_e32 v56, 1.0, v56
	v_rcp_f32_e32 v56, v56
	s_nop 0
	v_mul_f32_e32 v56, v65, v56
	v_mul_f32_e32 v56, v57, v56
	v_cvt_pk_bf16_f32 v55, v55, v56
	v_pk_mul_f32 v[56:57], v[58:59], v[66:67] op_sel_hi:[1,0]
	s_nop 0
	v_mul_f32_e32 v58, 0xbfb8aa3b, v56
	v_exp_f32_e32 v58, v58
	s_nop 0
	v_add_f32_e32 v58, 1.0, v58
	v_rcp_f32_e32 v58, v58
	s_nop 0
	v_mul_f32_e32 v56, v56, v58
	v_mul_f32_e32 v50, v50, v56
	v_mul_f32_e32 v56, 0xbfb8aa3b, v57
	v_exp_f32_e32 v56, v56
	s_nop 0
	v_add_f32_e32 v56, 1.0, v56
	v_rcp_f32_e32 v56, v56
	s_nop 0
	v_mul_f32_e32 v56, v57, v56
	v_mul_f32_e32 v51, v51, v56
	v_cvt_pk_bf16_f32 v56, v50, v51
	v_mul_f32_e32 v50, 0xbfb8aa3b, v60
	v_mul_f32_e32 v51, 0xbfb8aa3b, v61
	v_exp_f32_e32 v50, v50
	v_exp_f32_e32 v51, v51
	v_add_f32_e32 v50, 1.0, v50
	v_add_f32_e32 v51, 1.0, v51
	v_rcp_f32_e32 v50, v50
	v_rcp_f32_e32 v51, v51
	v_mul_f32_e32 v50, v60, v50
	v_mul_f32_e32 v51, v61, v51
	v_mul_f32_e32 v50, v52, v50
	v_mul_f32_e32 v51, v53, v51
	v_cvt_pk_bf16_f32 v57, v50, v51
	v_mad_i64_i32 v[50:51], s[4:5], v68, s2, v[114:115]
	v_lshl_add_u64 v[50:51], v[50:51], 0, v[116:117]
	global_store_dwordx4 v[50:51], v[54:57], off
	s_nop 1
	v_mov_b64_e32 v[50:51], v[182:183]
	v_add_u32_e32 v52, 0x90, v140
	v_ffbh_u32_e32 v53, v51
	v_min_u32_e32 v53, 32, v53
	v_lshlrev_b64 v[50:51], v53, v[50:51]
	v_min_u32_e32 v50, 1, v50
	v_or_b32_e32 v50, v51, v50
	v_cvt_f32_u32_e32 v50, v50
	v_sub_u32_e32 v51, 32, v53
	v_ldexp_f32 v50, v50, v51
	v_fmamk_f32 v50, v50, 0x2e800000, v143
	v_cmp_gt_f32_e32 vcc, s90, v50
	v_mul_f32_e32 v51, 0x4b800000, v50
	s_nop 0
	v_cndmask_b32_e32 v50, v50, v51, vcc
	v_rsq_f32_e32 v50, v50
	s_nop 0
	v_mul_f32_e32 v51, 0x45800000, v50
	v_cndmask_b32_e32 v50, v50, v51, vcc
	v_pk_mul_f32 v[46:47], v[46:47], v[50:51] op_sel_hi:[1,0]
	v_pk_mul_f32 v[48:49], v[48:49], v[50:51] op_sel_hi:[1,0]
	v_pk_mul_f32 v[40:41], v[40:41], v[50:51] op_sel_hi:[1,0]
	v_pk_mul_f32 v[38:39], v[38:39], v[50:51] op_sel_hi:[1,0]
	v_mul_f32_e32 v51, 0xbfb8aa3b, v46
	v_exp_f32_e32 v51, v51
	s_nop 0
	v_add_f32_e32 v51, 1.0, v51
	v_rcp_f32_e32 v51, v51
	s_nop 0
	v_mul_f32_e32 v46, v46, v51
	v_mul_f32_e32 v38, v38, v46
	v_mul_f32_e32 v46, 0xbfb8aa3b, v47
	v_exp_f32_e32 v46, v46
	v_pk_mul_f32 v[34:35], v[34:35], v[50:51] op_sel_hi:[1,0]
	v_pk_mul_f32 v[44:45], v[44:45], v[50:51] op_sel_hi:[1,0]
	v_pk_mul_f32 v[36:37], v[36:37], v[50:51] op_sel_hi:[1,0]
	v_add_f32_e32 v46, 1.0, v46
	v_rcp_f32_e32 v46, v46
	s_nop 0
	v_mul_f32_e32 v46, v47, v46
	v_mul_f32_e32 v39, v39, v46
	v_cvt_pk_bf16_f32 v38, v38, v39
	v_mul_f32_e32 v39, 0xbfb8aa3b, v48
	v_exp_f32_e32 v39, v39
	s_nop 0
	v_add_f32_e32 v39, 1.0, v39
	v_rcp_f32_e32 v39, v39
	s_nop 0
	v_mul_f32_e32 v39, v48, v39
	v_mul_f32_e32 v39, v40, v39
	v_mul_f32_e32 v40, 0xbfb8aa3b, v49
	v_exp_f32_e32 v40, v40
	s_nop 0
	v_add_f32_e32 v40, 1.0, v40
	v_rcp_f32_e32 v40, v40
	s_nop 0
	v_mul_f32_e32 v40, v49, v40
	v_mul_f32_e32 v40, v41, v40
	v_cvt_pk_bf16_f32 v39, v39, v40
	v_pk_mul_f32 v[40:41], v[42:43], v[50:51] op_sel_hi:[1,0]
	s_nop 0
	v_mul_f32_e32 v42, 0xbfb8aa3b, v40
	v_exp_f32_e32 v42, v42
	s_nop 0
	v_add_f32_e32 v42, 1.0, v42
	v_rcp_f32_e32 v42, v42
	s_nop 0
	v_mul_f32_e32 v40, v40, v42
	v_mul_f32_e32 v34, v34, v40
	v_mul_f32_e32 v40, 0xbfb8aa3b, v41
	v_exp_f32_e32 v40, v40
	s_nop 0
	v_add_f32_e32 v40, 1.0, v40
	v_rcp_f32_e32 v40, v40
	s_nop 0
	v_mul_f32_e32 v40, v41, v40
	v_mul_f32_e32 v35, v35, v40
	v_cvt_pk_bf16_f32 v40, v34, v35
	v_mul_f32_e32 v34, 0xbfb8aa3b, v44
	v_mul_f32_e32 v35, 0xbfb8aa3b, v45
	v_exp_f32_e32 v34, v34
	v_exp_f32_e32 v35, v35
	v_add_f32_e32 v34, 1.0, v34
	v_add_f32_e32 v35, 1.0, v35
	v_rcp_f32_e32 v34, v34
	v_rcp_f32_e32 v35, v35
	v_mul_f32_e32 v34, v44, v34
	v_mul_f32_e32 v35, v45, v35
	v_mul_f32_e32 v34, v36, v34
	v_mul_f32_e32 v35, v37, v35
	v_cvt_pk_bf16_f32 v41, v34, v35
	v_mad_i64_i32 v[34:35], s[4:5], v52, s2, v[114:115]
	v_lshl_add_u64 v[34:35], v[34:35], 0, v[116:117]
	global_store_dwordx4 v[34:35], v[38:41], off
	s_nop 1
	v_mov_b64_e32 v[34:35], v[216:217]
	v_mov_b32_e32 v216, 0
	v_mov_b32_e32 v217, 0
	v_add_u32_e32 v36, 0xa0, v140
	v_ffbh_u32_e32 v37, v35
	v_min_u32_e32 v37, 32, v37
	v_lshlrev_b64 v[34:35], v37, v[34:35]
	v_min_u32_e32 v34, 1, v34
	v_or_b32_e32 v34, v35, v34
	v_cvt_f32_u32_e32 v34, v34
	v_sub_u32_e32 v35, 32, v37
	v_ldexp_f32 v34, v34, v35
	v_fmamk_f32 v34, v34, 0x2e800000, v143
	v_cmp_gt_f32_e32 vcc, s90, v34
	v_mul_f32_e32 v35, 0x4b800000, v34
	s_nop 0
	v_cndmask_b32_e32 v34, v34, v35, vcc
	v_rsq_f32_e32 v34, v34
	s_nop 0
	v_mul_f32_e32 v35, 0x45800000, v34
	v_cndmask_b32_e32 v34, v34, v35, vcc
	v_pk_mul_f32 v[30:31], v[30:31], v[34:35] op_sel_hi:[1,0]
	v_pk_mul_f32 v[32:33], v[32:33], v[34:35] op_sel_hi:[1,0]
	v_pk_mul_f32 v[24:25], v[24:25], v[34:35] op_sel_hi:[1,0]
	v_pk_mul_f32 v[22:23], v[22:23], v[34:35] op_sel_hi:[1,0]
	v_mul_f32_e32 v35, 0xbfb8aa3b, v30
	v_exp_f32_e32 v35, v35
	s_nop 0
	v_add_f32_e32 v35, 1.0, v35
	v_rcp_f32_e32 v35, v35
	s_nop 0
	v_mul_f32_e32 v30, v30, v35
	v_mul_f32_e32 v22, v22, v30
	v_mul_f32_e32 v30, 0xbfb8aa3b, v31
	v_exp_f32_e32 v30, v30
	v_pk_mul_f32 v[18:19], v[18:19], v[34:35] op_sel_hi:[1,0]
	v_pk_mul_f32 v[28:29], v[28:29], v[34:35] op_sel_hi:[1,0]
	v_pk_mul_f32 v[20:21], v[20:21], v[34:35] op_sel_hi:[1,0]
	v_add_f32_e32 v30, 1.0, v30
	v_rcp_f32_e32 v30, v30
	s_nop 0
	v_mul_f32_e32 v30, v31, v30
	v_mul_f32_e32 v23, v23, v30
	v_cvt_pk_bf16_f32 v22, v22, v23
	v_mul_f32_e32 v23, 0xbfb8aa3b, v32
	v_exp_f32_e32 v23, v23
	s_nop 0
	v_add_f32_e32 v23, 1.0, v23
	v_rcp_f32_e32 v23, v23
	s_nop 0
	v_mul_f32_e32 v23, v32, v23
	v_mul_f32_e32 v23, v24, v23
	v_mul_f32_e32 v24, 0xbfb8aa3b, v33
	v_exp_f32_e32 v24, v24
	s_nop 0
	v_add_f32_e32 v24, 1.0, v24
	v_rcp_f32_e32 v24, v24
	s_nop 0
	v_mul_f32_e32 v24, v33, v24
	v_mul_f32_e32 v24, v25, v24
	v_cvt_pk_bf16_f32 v23, v23, v24
	v_pk_mul_f32 v[24:25], v[26:27], v[34:35] op_sel_hi:[1,0]
	s_nop 0
	v_mul_f32_e32 v26, 0xbfb8aa3b, v24
	v_exp_f32_e32 v26, v26
	s_nop 0
	v_add_f32_e32 v26, 1.0, v26
	v_rcp_f32_e32 v26, v26
	s_nop 0
	v_mul_f32_e32 v24, v24, v26
	v_mul_f32_e32 v18, v18, v24
	v_mul_f32_e32 v24, 0xbfb8aa3b, v25
	v_exp_f32_e32 v24, v24
	s_nop 0
	v_add_f32_e32 v24, 1.0, v24
	v_rcp_f32_e32 v24, v24
	s_nop 0
	v_mul_f32_e32 v24, v25, v24
	v_mul_f32_e32 v19, v19, v24
	v_cvt_pk_bf16_f32 v24, v18, v19
	v_mul_f32_e32 v18, 0xbfb8aa3b, v28
	v_mul_f32_e32 v19, 0xbfb8aa3b, v29
	v_exp_f32_e32 v18, v18
	v_exp_f32_e32 v19, v19
	v_add_f32_e32 v18, 1.0, v18
	v_add_f32_e32 v19, 1.0, v19
	v_rcp_f32_e32 v18, v18
	v_rcp_f32_e32 v19, v19
	v_mul_f32_e32 v18, v28, v18
	v_mul_f32_e32 v19, v29, v19
	v_mul_f32_e32 v18, v20, v18
	v_mul_f32_e32 v19, v21, v19
	v_cvt_pk_bf16_f32 v25, v18, v19
	v_mad_i64_i32 v[18:19], s[4:5], v36, s2, v[114:115]
	v_lshl_add_u64 v[18:19], v[18:19], 0, v[116:117]
	global_store_dwordx4 v[18:19], v[22:25], off
	s_nop 1
	v_mov_b64_e32 v[18:19], v[242:243]
	v_add_u32_e32 v20, 0xb0, v140
	v_ffbh_u32_e32 v21, v19
	v_min_u32_e32 v21, 32, v21
	v_lshlrev_b64 v[18:19], v21, v[18:19]
	v_min_u32_e32 v18, 1, v18
	v_or_b32_e32 v18, v19, v18
	v_cvt_f32_u32_e32 v18, v18
	v_sub_u32_e32 v19, 32, v21
	v_ldexp_f32 v18, v18, v19
	v_fmamk_f32 v18, v18, 0x2e800000, v143
	v_cmp_gt_f32_e32 vcc, s90, v18
	v_mul_f32_e32 v19, 0x4b800000, v18
	s_nop 0
	v_cndmask_b32_e32 v18, v18, v19, vcc
	v_rsq_f32_e32 v18, v18
	s_nop 0
	v_mul_f32_e32 v19, 0x45800000, v18
	v_cndmask_b32_e32 v18, v18, v19, vcc
	v_pk_mul_f32 v[14:15], v[14:15], v[18:19] op_sel_hi:[1,0]
	v_pk_mul_f32 v[16:17], v[16:17], v[18:19] op_sel_hi:[1,0]
	v_pk_mul_f32 v[8:9], v[8:9], v[18:19] op_sel_hi:[1,0]
	v_pk_mul_f32 v[6:7], v[6:7], v[18:19] op_sel_hi:[1,0]
	v_mul_f32_e32 v19, 0xbfb8aa3b, v14
	v_exp_f32_e32 v19, v19
	s_and_b64 vcc, exec, s[6:7]
	v_add_f32_e32 v19, 1.0, v19
	v_rcp_f32_e32 v19, v19
	s_nop 0
	v_mul_f32_e32 v14, v14, v19
	v_mul_f32_e32 v6, v6, v14
	v_mul_f32_e32 v14, 0xbfb8aa3b, v15
	v_exp_f32_e32 v14, v14
	v_pk_mul_f32 v[2:3], v[2:3], v[18:19] op_sel_hi:[1,0]
	v_pk_mul_f32 v[12:13], v[12:13], v[18:19] op_sel_hi:[1,0]
	v_pk_mul_f32 v[4:5], v[4:5], v[18:19] op_sel_hi:[1,0]
	v_add_f32_e32 v14, 1.0, v14
	v_rcp_f32_e32 v14, v14
	s_nop 0
	v_mul_f32_e32 v14, v15, v14
	v_mul_f32_e32 v7, v7, v14
	v_cvt_pk_bf16_f32 v6, v6, v7
	v_mul_f32_e32 v7, 0xbfb8aa3b, v16
	v_exp_f32_e32 v7, v7
	s_nop 0
	v_add_f32_e32 v7, 1.0, v7
	v_rcp_f32_e32 v7, v7
	s_nop 0
	v_mul_f32_e32 v7, v16, v7
	v_mul_f32_e32 v7, v8, v7
	v_mul_f32_e32 v8, 0xbfb8aa3b, v17
	v_exp_f32_e32 v8, v8
	s_nop 0
	v_add_f32_e32 v8, 1.0, v8
	v_rcp_f32_e32 v8, v8
	s_nop 0
	v_mul_f32_e32 v8, v17, v8
	v_mul_f32_e32 v8, v9, v8
	v_cvt_pk_bf16_f32 v7, v7, v8
	v_pk_mul_f32 v[8:9], v[10:11], v[18:19] op_sel_hi:[1,0]
	s_nop 0
	v_mul_f32_e32 v10, 0xbfb8aa3b, v8
	v_exp_f32_e32 v10, v10
	s_nop 0
	v_add_f32_e32 v10, 1.0, v10
	v_rcp_f32_e32 v10, v10
	s_nop 0
	v_mul_f32_e32 v8, v8, v10
	v_mul_f32_e32 v2, v2, v8
	v_mul_f32_e32 v8, 0xbfb8aa3b, v9
	v_exp_f32_e32 v8, v8
	s_nop 0
	v_add_f32_e32 v8, 1.0, v8
	v_rcp_f32_e32 v8, v8
	s_nop 0
	v_mul_f32_e32 v8, v9, v8
	v_mul_f32_e32 v3, v3, v8
	v_cvt_pk_bf16_f32 v8, v2, v3
	v_mul_f32_e32 v2, 0xbfb8aa3b, v12
	v_mul_f32_e32 v3, 0xbfb8aa3b, v13
	v_exp_f32_e32 v2, v2
	v_exp_f32_e32 v3, v3
	v_add_f32_e32 v2, 1.0, v2
	v_add_f32_e32 v3, 1.0, v3
	v_rcp_f32_e32 v2, v2
	v_rcp_f32_e32 v3, v3
	v_mul_f32_e32 v2, v12, v2
	v_mul_f32_e32 v3, v13, v3
	v_mul_f32_e32 v2, v4, v2
	v_mul_f32_e32 v3, v5, v3
	v_cvt_pk_bf16_f32 v9, v2, v3
	v_mad_i64_i32 v[2:3], s[4:5], v20, s2, v[114:115]
	v_lshl_add_u64 v[2:3], v[2:3], 0, v[116:117]
	s_mov_b32 s4, s8
	s_mov_b32 s2, s12
	global_store_dwordx4 v[2:3], v[6:9], off
	s_cbranch_vccz .LBB0_122
	s_waitcnt vmcnt(0)
	s_cmpk_gt_u32 s26, 0xff
	s_cbranch_scc1 .LBB0_129
	s_barrier
